# re-measure: 128 s_nop executed before each in-loop grid sync (on top of v16)
# speedup vs baseline: 1.0150x; 1.0041x over previous
.LBB0_194:
	s_nop 0
	s_nop 0
	s_nop 0
	s_nop 0
	s_nop 0
	s_nop 0
	s_nop 0
	s_nop 0
	s_nop 0
	s_nop 0
	s_nop 0
	s_nop 0
	s_nop 0
	s_nop 0
	s_nop 0
	s_nop 0
	s_nop 0
	s_nop 0
	s_nop 0
	s_nop 0
	s_nop 0
	s_nop 0
	s_nop 0
	s_nop 0
	s_nop 0
	s_nop 0
	s_nop 0
	s_nop 0
	s_nop 0
	s_nop 0
	s_nop 0
	s_nop 0
	s_nop 0
	s_nop 0
	s_nop 0
	s_nop 0
	s_nop 0
	s_nop 0
	s_nop 0
	s_nop 0
	s_nop 0
	s_nop 0
	s_nop 0
	s_nop 0
	s_nop 0
	s_nop 0
	s_nop 0
	s_nop 0
	s_nop 0
	s_nop 0
	s_nop 0
	s_nop 0
	s_nop 0
	s_nop 0
	s_nop 0
	s_nop 0
	s_nop 0
	s_nop 0
	s_nop 0
	s_nop 0
	s_nop 0
	s_nop 0
	s_nop 0
	s_nop 0
	s_nop 0
	s_nop 0
	s_nop 0
	s_nop 0
	s_nop 0
	s_nop 0
	s_nop 0
	s_nop 0
	s_nop 0
	s_nop 0
	s_nop 0
	s_nop 0
	s_nop 0
	s_nop 0
	s_nop 0
	s_nop 0
	s_nop 0
	s_nop 0
	s_nop 0
	s_nop 0
	s_nop 0
	s_nop 0
	s_nop 0
	s_nop 0
	s_nop 0
	s_nop 0
	s_nop 0
	s_nop 0
	s_nop 0
	s_nop 0
	s_nop 0
	s_nop 0
	s_nop 0
	s_nop 0
	s_nop 0
	s_nop 0
	s_nop 0
	s_nop 0
	s_nop 0
	s_nop 0
	s_nop 0
	s_nop 0
	s_nop 0
	s_nop 0
	s_nop 0
	s_nop 0
	s_nop 0
	s_nop 0
	s_nop 0
	s_nop 0
	s_nop 0
	s_nop 0
	s_nop 0
	s_nop 0
	s_nop 0
	s_nop 0
	s_nop 0
	s_nop 0
	s_nop 0
	s_nop 0
	s_nop 0
	s_nop 0
	s_nop 0
	s_nop 0
	s_waitcnt vmcnt(0)
	s_barrier
	s_and_saveexec_b64 s[2:3], s[82:83]
	s_movk_i32 s56, 0x4000
	s_movk_i32 s57, 0x90
	s_movk_i32 s96, 0x1000
	s_movk_i32 s97, 0x408
	s_cbranch_execz .LBB0_246
	v_readlane_b32 s0, v253, 43
	s_waitcnt vmcnt(0) expcnt(0) lgkmcnt(0)
	s_nop 0
	v_mov_b32_e32 v0, s0
	ds_read_b32 v3, v0
	v_readlane_b32 s0, v253, 44
	s_waitcnt lgkmcnt(0)
	v_cmp_ne_u32_e32 vcc, 0, v3
	v_mov_b32_e32 v0, s0
	ds_read_b32 v2, v0
	s_cbranch_vccnz .LBB0_210
	s_mov_b32 s8, 1
	s_branch .LBB0_198

.LBB0_266:
	s_nop 0
	s_nop 0
	s_nop 0
	s_nop 0
	s_nop 0
	s_nop 0
	s_nop 0
	s_nop 0
	s_nop 0
	s_nop 0
	s_nop 0
	s_nop 0
	s_nop 0
	s_nop 0
	s_nop 0
	s_nop 0
	s_nop 0
	s_nop 0
	s_nop 0
	s_nop 0
	s_nop 0
	s_nop 0
	s_nop 0
	s_nop 0
	s_nop 0
	s_nop 0
	s_nop 0
	s_nop 0
	s_nop 0
	s_nop 0
	s_nop 0
	s_nop 0
	s_nop 0
	s_nop 0
	s_nop 0
	s_nop 0
	s_nop 0
	s_nop 0
	s_nop 0
	s_nop 0
	s_nop 0
	s_nop 0
	s_nop 0
	s_nop 0
	s_nop 0
	s_nop 0
	s_nop 0
	s_nop 0
	s_nop 0
	s_nop 0
	s_nop 0
	s_nop 0
	s_nop 0
	s_nop 0
	s_nop 0
	s_nop 0
	s_nop 0
	s_nop 0
	s_nop 0
	s_nop 0
	s_nop 0
	s_nop 0
	s_nop 0
	s_nop 0
	s_nop 0
	s_nop 0
	s_nop 0
	s_nop 0
	s_nop 0
	s_nop 0
	s_nop 0
	s_nop 0
	s_nop 0
	s_nop 0
	s_nop 0
	s_nop 0
	s_nop 0
	s_nop 0
	s_nop 0
	s_nop 0
	s_nop 0
	s_nop 0
	s_nop 0
	s_nop 0
	s_nop 0
	s_nop 0
	s_nop 0
	s_nop 0
	s_nop 0
	s_nop 0
	s_nop 0
	s_nop 0
	s_nop 0
	s_nop 0
	s_nop 0
	s_nop 0
	s_nop 0
	s_nop 0
	s_nop 0
	s_nop 0
	s_nop 0
	s_nop 0
	s_nop 0
	s_nop 0
	s_nop 0
	s_nop 0
	s_nop 0
	s_nop 0
	s_nop 0
	s_nop 0
	s_nop 0
	s_nop 0
	s_nop 0
	s_nop 0
	s_nop 0
	s_nop 0
	s_nop 0
	s_nop 0
	s_nop 0
	s_nop 0
	s_nop 0
	s_nop 0
	s_nop 0
	s_nop 0
	s_nop 0
	s_nop 0
	s_nop 0
	s_nop 0
	s_waitcnt vmcnt(0)
	s_waitcnt vmcnt(0)
	s_barrier
	s_and_saveexec_b64 s[2:3], s[82:83]
	s_cbranch_execz .LBB0_318
	v_readlane_b32 s0, v253, 43
	s_waitcnt vmcnt(0) expcnt(0) lgkmcnt(0)
	s_nop 0
	v_mov_b32_e32 v0, s0
	ds_read_b32 v3, v0
	v_readlane_b32 s0, v253, 44
	s_waitcnt lgkmcnt(0)
	v_cmp_ne_u32_e32 vcc, 0, v3
	v_mov_b32_e32 v0, s0
	ds_read_b32 v2, v0
	s_cbranch_vccnz .LBB0_282
	s_mov_b32 s8, 1
	s_branch .LBB0_270

.LBB0_360:
	s_nop 0
	s_nop 0
	s_nop 0
	s_nop 0
	s_nop 0
	s_nop 0
	s_nop 0
	s_nop 0
	s_nop 0
	s_nop 0
	s_nop 0
	s_nop 0
	s_nop 0
	s_nop 0
	s_nop 0
	s_nop 0
	s_nop 0
	s_nop 0
	s_nop 0
	s_nop 0
	s_nop 0
	s_nop 0
	s_nop 0
	s_nop 0
	s_nop 0
	s_nop 0
	s_nop 0
	s_nop 0
	s_nop 0
	s_nop 0
	s_nop 0
	s_nop 0
	s_nop 0
	s_nop 0
	s_nop 0
	s_nop 0
	s_nop 0
	s_nop 0
	s_nop 0
	s_nop 0
	s_nop 0
	s_nop 0
	s_nop 0
	s_nop 0
	s_nop 0
	s_nop 0
	s_nop 0
	s_nop 0
	s_nop 0
	s_nop 0
	s_nop 0
	s_nop 0
	s_nop 0
	s_nop 0
	s_nop 0
	s_nop 0
	s_nop 0
	s_nop 0
	s_nop 0
	s_nop 0
	s_nop 0
	s_nop 0
	s_nop 0
	s_nop 0
	s_nop 0
	s_nop 0
	s_nop 0
	s_nop 0
	s_nop 0
	s_nop 0
	s_nop 0
	s_nop 0
	s_nop 0
	s_nop 0
	s_nop 0
	s_nop 0
	s_nop 0
	s_nop 0
	s_nop 0
	s_nop 0
	s_nop 0
	s_nop 0
	s_nop 0
	s_nop 0
	s_nop 0
	s_nop 0
	s_nop 0
	s_nop 0
	s_nop 0
	s_nop 0
	s_nop 0
	s_nop 0
	s_nop 0
	s_nop 0
	s_nop 0
	s_nop 0
	s_nop 0
	s_nop 0
	s_nop 0
	s_nop 0
	s_nop 0
	s_nop 0
	s_nop 0
	s_nop 0
	s_nop 0
	s_nop 0
	s_nop 0
	s_nop 0
	s_nop 0
	s_nop 0
	s_nop 0
	s_nop 0
	s_nop 0
	s_nop 0
	s_nop 0
	s_nop 0
	s_nop 0
	s_nop 0
	s_nop 0
	s_nop 0
	s_nop 0
	s_nop 0
	s_nop 0
	s_nop 0
	s_nop 0
	s_nop 0
	s_nop 0
	s_nop 0
	s_waitcnt vmcnt(0)
	s_barrier
	s_and_saveexec_b64 s[2:3], s[82:83]
	s_cbranch_execz .LBB0_458
	v_readlane_b32 s0, v253, 43
	s_waitcnt vmcnt(0) expcnt(0) lgkmcnt(0)
	s_nop 0
	v_mov_b32_e32 v0, s0
	ds_read_b32 v3, v0
	v_readlane_b32 s0, v253, 44
	s_waitcnt lgkmcnt(0)
	v_cmp_ne_u32_e32 vcc, 0, v3
	v_mov_b32_e32 v0, s0
	ds_read_b32 v2, v0
	s_cbranch_vccnz .LBB0_422
	s_mov_b32 s8, 1
	s_branch .LBB0_410

.LBB0_1271:
	s_nop 0
	s_nop 0
	s_nop 0
	s_nop 0
	s_nop 0
	s_nop 0
	s_nop 0
	s_nop 0
	s_nop 0
	s_nop 0
	s_nop 0
	s_nop 0
	s_nop 0
	s_nop 0
	s_nop 0
	s_nop 0
	s_nop 0
	s_nop 0
	s_nop 0
	s_nop 0
	s_nop 0
	s_nop 0
	s_nop 0
	s_nop 0
	s_nop 0
	s_nop 0
	s_nop 0
	s_nop 0
	s_nop 0
	s_nop 0
	s_nop 0
	s_nop 0
	s_nop 0
	s_nop 0
	s_nop 0
	s_nop 0
	s_nop 0
	s_nop 0
	s_nop 0
	s_nop 0
	s_nop 0
	s_nop 0
	s_nop 0
	s_nop 0
	s_nop 0
	s_nop 0
	s_nop 0
	s_nop 0
	s_nop 0
	s_nop 0
	s_nop 0
	s_nop 0
	s_nop 0
	s_nop 0
	s_nop 0
	s_nop 0
	s_nop 0
	s_nop 0
	s_nop 0
	s_nop 0
	s_nop 0
	s_nop 0
	s_nop 0
	s_nop 0
	s_nop 0
	s_nop 0
	s_nop 0
	s_nop 0
	s_nop 0
	s_nop 0
	s_nop 0
	s_nop 0
	s_nop 0
	s_nop 0
	s_nop 0
	s_nop 0
	s_nop 0
	s_nop 0
	s_nop 0
	s_nop 0
	s_nop 0
	s_nop 0
	s_nop 0
	s_nop 0
	s_nop 0
	s_nop 0
	s_nop 0
	s_nop 0
	s_nop 0
	s_nop 0
	s_nop 0
	s_nop 0
	s_nop 0
	s_nop 0
	s_nop 0
	s_nop 0
	s_nop 0
	s_nop 0
	s_nop 0
	s_nop 0
	s_nop 0
	s_nop 0
	s_nop 0
	s_nop 0
	s_nop 0
	s_nop 0
	s_nop 0
	s_nop 0
	s_nop 0
	s_nop 0
	s_nop 0
	s_nop 0
	s_nop 0
	s_nop 0
	s_nop 0
	s_nop 0
	s_nop 0
	s_nop 0
	s_nop 0
	s_nop 0
	s_nop 0
	s_nop 0
	s_nop 0
	s_nop 0
	s_nop 0
	s_nop 0
	s_nop 0
	s_nop 0
	s_waitcnt vmcnt(0)
	s_barrier
	s_and_saveexec_b64 s[2:3], s[82:83]
	s_cbranch_execnz .LBB0_1272
	s_getpc_b64 s[98:99]
